# P3 loop: DMA pointer advances moved from the pre-barrier tail into the first p0-chain gap
# baseline (speedup 1.0000x reference)
.LBB0_325:
	s_waitcnt lgkmcnt(4)
	v_mfma_f32_32x32x16_bf16 v[96:111], v[80:83], v[144:147], v[64:79]
	v_lshl_add_u64 v[218:219], v[218:219], 0, s[88:89]
	v_lshl_add_u64 v[220:221], v[220:221], 0, s[88:89]
	v_lshl_add_u64 v[224:225], v[224:225], 0, s[92:93]
	v_mfma_f32_32x32x16_bf16 v[96:111], v[202:205], v[140:143], v[96:111]
	s_add_i32 s4, s100, 64
	v_cvt_f32_i32_e32 v156, s4
	v_add_f32_e32 v156, v255, v156
	v_fma_f32 v254, v208, v156, -v207
	s_nop 0
	v_mfma_f32_32x32x16_bf16 v[96:111], v[194:197], v[136:139], v[96:111]
	v_mov_b32_e32 v64, v254
	v_fmamk_f32 v65, v208, 0x3f800000, v254
	v_fmamk_f32 v66, v208, 0x40000000, v254
	v_fmamk_f32 v67, v208, 0x40400000, v254
	v_fmamk_f32 v68, v208, 0x41000000, v254
	v_fmamk_f32 v69, v208, 0x41100000, v254
	v_fmamk_f32 v70, v208, 0x41200000, v254
	v_fmamk_f32 v71, v208, 0x41300000, v254
	v_mfma_f32_32x32x16_bf16 v[96:111], v[186:189], v[132:135], v[96:111]
	v_fmamk_f32 v72, v208, 0x41800000, v254
	v_fmamk_f32 v73, v208, 0x41880000, v254
	v_fmamk_f32 v74, v208, 0x41900000, v254
	v_fmamk_f32 v75, v208, 0x41980000, v254
	v_fmamk_f32 v76, v208, 0x41c00000, v254
	v_fmamk_f32 v77, v208, 0x41c80000, v254
	v_fmamk_f32 v78, v208, 0x41d00000, v254
	v_fmamk_f32 v79, v208, 0x41d80000, v254
	s_add_i32 s3, s79, 0xfffe8000
	s_and_b32 s3, s3, 0x18000
	v_add_u32_e32 v158, s3, v235
	v_add_u32_e32 v159, s3, v239
	v_add_u32_e32 v160, s3, v236
	v_add_u32_e32 v161, s3, v234
	ds_read_b64_tr_b16 v[182:183], v158 offset:32768
	ds_read_b64_tr_b16 v[184:185], v158 offset:34816
	ds_read_b64_tr_b16 v[178:179], v159 offset:32768
	ds_read_b64_tr_b16 v[180:181], v159 offset:34816
	ds_read_b64_tr_b16 v[148:149], v160 offset:32768
	ds_read_b64_tr_b16 v[150:151], v160 offset:34816
	ds_read_b64_tr_b16 v[152:153], v161 offset:32768
	ds_read_b64_tr_b16 v[154:155], v161 offset:34816
	s_waitcnt lgkmcnt(8)
	v_mfma_f32_32x32x16_bf16 v[80:95], v[198:201], v[144:147], v[64:79]
	v_exp_f32_e32 v96, v96
	v_exp_f32_e32 v97, v97
	v_exp_f32_e32 v98, v98
	v_exp_f32_e32 v99, v99
	v_mfma_f32_32x32x16_bf16 v[80:95], v[190:193], v[140:143], v[80:95]
	v_exp_f32_e32 v100, v100
	v_exp_f32_e32 v101, v101
	v_exp_f32_e32 v102, v102
	v_exp_f32_e32 v103, v103
	v_mfma_f32_32x32x16_bf16 v[80:95], v[246:249], v[136:139], v[80:95]
	v_exp_f32_e32 v104, v104
	v_exp_f32_e32 v105, v105
	v_exp_f32_e32 v106, v106
	v_exp_f32_e32 v107, v107
	v_mfma_f32_32x32x16_bf16 v[80:95], v[250:253], v[132:135], v[80:95]
	v_exp_f32_e32 v108, v108
	v_exp_f32_e32 v109, v109
	v_exp_f32_e32 v110, v110
	v_exp_f32_e32 v111, v111
	s_nop 3
	s_cmp_le_i32 s72, s101
	s_cbranch_scc0 .Lmask_blk
.LBB0_327:
	s_waitcnt lgkmcnt(4)
	v_mfma_f32_32x32x16_bf16 v[48:63], v[182:185], v[174:177], v[48:63]
	v_sub_f32_e32 v190, v80, v237
	v_exp_f32_e32 v190, v190
	ds_read_b64_tr_b16 v[246:247], v158 offset:36864
	ds_read_b64_tr_b16 v[248:249], v158 offset:38912
	v_add_f32_e32 v157, v190, v96
	v_mfma_f32_32x32x16_bf16 v[32:47], v[178:181], v[174:177], v[32:47]
	v_sub_f32_e32 v191, v81, v237
	v_exp_f32_e32 v191, v191
	ds_read_b64_tr_b16 v[250:251], v159 offset:36864
	ds_read_b64_tr_b16 v[252:253], v159 offset:38912
	v_add_f32_e32 v156, v191, v97
	v_add_f32_e32 v157, v156, v157
	s_waitcnt lgkmcnt(4)
	v_mfma_f32_32x32x16_bf16 v[16:31], v[148:151], v[174:177], v[16:31]
	v_sub_f32_e32 v192, v82, v237
	v_exp_f32_e32 v192, v192
	ds_read_b64_tr_b16 v[182:183], v160 offset:36864
	ds_read_b64_tr_b16 v[184:185], v160 offset:38912
	v_add_f32_e32 v156, v192, v98
	v_add_f32_e32 v157, v156, v157
	v_mfma_f32_32x32x16_bf16 v[0:15], v[152:155], v[174:177], v[0:15]
	v_sub_f32_e32 v193, v83, v237
	v_exp_f32_e32 v193, v193
	ds_read_b64_tr_b16 v[178:179], v161 offset:36864
	ds_read_b64_tr_b16 v[180:181], v161 offset:38912
	v_add_f32_e32 v156, v193, v99
	v_add_f32_e32 v157, v156, v157
	v_cvt_pk_bf16_f32 v174, v96, v97
	s_waitcnt lgkmcnt(4)
	v_mfma_f32_32x32x16_bf16 v[48:63], v[246:249], v[162:165], v[48:63]
	v_sub_f32_e32 v194, v84, v237
	v_exp_f32_e32 v194, v194
	ds_read_b64_tr_b16 v[148:149], v158 offset:40960
	ds_read_b64_tr_b16 v[150:151], v158 offset:43008
	v_add_f32_e32 v156, v194, v100
	v_add_f32_e32 v157, v156, v157
	v_cvt_pk_bf16_f32 v175, v98, v99
	v_mfma_f32_32x32x16_bf16 v[32:47], v[250:253], v[162:165], v[32:47]
	v_sub_f32_e32 v195, v85, v237
	v_exp_f32_e32 v195, v195
	ds_read_b64_tr_b16 v[152:153], v159 offset:40960
	ds_read_b64_tr_b16 v[154:155], v159 offset:43008
	v_add_f32_e32 v156, v195, v101
	v_add_f32_e32 v157, v156, v157
	v_cvt_pk_bf16_f32 v176, v100, v101
	s_waitcnt lgkmcnt(4)
	v_mfma_f32_32x32x16_bf16 v[16:31], v[182:185], v[162:165], v[16:31]
	v_sub_f32_e32 v196, v86, v237
	v_exp_f32_e32 v196, v196
	ds_read_b64_tr_b16 v[246:247], v160 offset:40960
	ds_read_b64_tr_b16 v[248:249], v160 offset:43008
	v_add_f32_e32 v156, v196, v102
	v_add_f32_e32 v157, v156, v157
	v_cvt_pk_bf16_f32 v177, v102, v103
	v_mfma_f32_32x32x16_bf16 v[0:15], v[178:181], v[162:165], v[0:15]
	v_sub_f32_e32 v197, v87, v237
	v_exp_f32_e32 v197, v197
	ds_read_b64_tr_b16 v[250:251], v161 offset:40960
	ds_read_b64_tr_b16 v[252:253], v161 offset:43008
	v_add_f32_e32 v156, v197, v103
	v_add_f32_e32 v157, v156, v157
	v_cvt_pk_bf16_f32 v162, v104, v105
	s_waitcnt lgkmcnt(4)
	v_mfma_f32_32x32x16_bf16 v[48:63], v[148:151], v[170:173], v[48:63]
	v_sub_f32_e32 v198, v88, v237
	v_exp_f32_e32 v198, v198
	ds_read_b64_tr_b16 v[182:183], v158 offset:45056
	ds_read_b64_tr_b16 v[184:185], v158 offset:47104
	v_add_f32_e32 v156, v198, v104
	v_add_f32_e32 v157, v156, v157
	v_cvt_pk_bf16_f32 v163, v106, v107
	v_mfma_f32_32x32x16_bf16 v[32:47], v[152:155], v[170:173], v[32:47]
	v_sub_f32_e32 v199, v89, v237
	v_exp_f32_e32 v199, v199
	ds_read_b64_tr_b16 v[178:179], v159 offset:45056
	ds_read_b64_tr_b16 v[180:181], v159 offset:47104
	v_add_f32_e32 v156, v199, v105
	v_add_f32_e32 v157, v156, v157
	v_cvt_pk_bf16_f32 v164, v108, v109
	s_waitcnt lgkmcnt(4)
	v_mfma_f32_32x32x16_bf16 v[16:31], v[246:249], v[170:173], v[16:31]
	v_sub_f32_e32 v200, v90, v237
	v_exp_f32_e32 v200, v200
	ds_read_b64_tr_b16 v[148:149], v160 offset:45056
	ds_read_b64_tr_b16 v[150:151], v160 offset:47104
	v_add_f32_e32 v156, v200, v106
	v_add_f32_e32 v157, v156, v157
	v_cvt_pk_bf16_f32 v165, v110, v111
	v_mfma_f32_32x32x16_bf16 v[0:15], v[250:253], v[170:173], v[0:15]
	v_sub_f32_e32 v201, v91, v237
	v_exp_f32_e32 v201, v201
	ds_read_b64_tr_b16 v[152:153], v161 offset:45056
	ds_read_b64_tr_b16 v[154:155], v161 offset:47104
	v_add_f32_e32 v156, v201, v107
	v_add_f32_e32 v157, v156, v157
	v_cvt_pk_bf16_f32 v170, v190, v191
	s_waitcnt lgkmcnt(4)
	v_mfma_f32_32x32x16_bf16 v[48:63], v[182:185], v[166:169], v[48:63]
	v_sub_f32_e32 v202, v92, v237
	v_exp_f32_e32 v202, v202
	v_cvt_pk_bf16_f32 v171, v192, v193
	v_add_f32_e32 v156, v202, v108
	v_add_f32_e32 v157, v156, v157
	v_mfma_f32_32x32x16_bf16 v[32:47], v[178:181], v[166:169], v[32:47]
	v_sub_f32_e32 v203, v93, v237
	v_exp_f32_e32 v203, v203
	v_cvt_pk_bf16_f32 v172, v194, v195
	v_add_f32_e32 v156, v203, v109
	v_add_f32_e32 v157, v156, v157
	s_waitcnt lgkmcnt(0)
	v_mfma_f32_32x32x16_bf16 v[16:31], v[148:151], v[166:169], v[16:31]
	v_sub_f32_e32 v204, v94, v237
	v_exp_f32_e32 v204, v204
	v_cvt_pk_bf16_f32 v173, v196, v197
	v_add_f32_e32 v156, v204, v110
	v_add_f32_e32 v157, v156, v157
	v_mfma_f32_32x32x16_bf16 v[0:15], v[152:155], v[166:169], v[0:15]
	v_sub_f32_e32 v205, v95, v237
	v_exp_f32_e32 v205, v205
	v_cvt_pk_bf16_f32 v166, v198, v199
	v_add_f32_e32 v156, v205, v111
	v_add_f32_e32 v157, v156, v157
	v_cvt_pk_bf16_f32 v167, v200, v201
	v_cvt_pk_bf16_f32 v168, v202, v203
	v_cvt_pk_bf16_f32 v169, v204, v205
	s_add_i32 s72, s72, 1
	s_add_i32 s79, s79, 0x8000
	s_add_i32 s100, s100, 64
	v_add_f32_e32 v229, v229, v157
	s_and_b32 s1, s79, 0x18000
	s_xor_b32 s0, s1, 0x10000
	v_add_u32_e32 v158, s0, v222
	v_add_u32_e32 v159, s0, v223
	v_add_u32_e32 v160, s0, v241
	v_add_u32_e32 v161, s0, v242
	s_cmp_ge_i32 s72, s99
	s_cbranch_scc1 .LBB0_332
	s_cmp_ge_i32 s72, s73
	s_cbranch_scc1 .Lk_last
	s_waitcnt vmcnt(4) lgkmcnt(0)
	s_barrier
	s_branch .Lk_top
